# w_out / w_down tile epilogue: the single wait after the 20 loads of the first half replaced by counted waits at first use (combine and stores start as the vectors land)
# baseline (speedup 1.0000x reference)
.LBB0_1499:
	s_andn2_b64 vcc, exec, s[42:43]
	s_cbranch_vccnz .LBB0_1501
	s_ashr_i32 s4, s38, 4
	s_mul_hi_i32 s27, s4, 0x18000
	s_mul_i32 s4, s4, 0x18000
	s_add_u32 s42, s10, s4
	s_addc_u32 s43, s11, s27
	s_ashr_i32 s39, s38, 31
	s_lshl_b64 s[38:39], s[38:39], 8
	s_add_u32 s38, s38, s68
	v_lshlrev_b64 v[14:15], 2, v[2:3]
	v_ashrrev_i32_e32 v5, 31, v4
	s_addc_u32 s39, s39, 0
	v_lshl_add_u64 v[16:17], s[42:43], 0, v[14:15]
	v_lshl_add_u64 v[22:23], s[38:39], 0, v[4:5]
	global_load_dwordx4 v[6:9], v[16:17], off
	global_load_dwordx4 v[10:13], v[16:17], off offset:64
	global_load_dwordx4 v[24:27], v[16:17], off offset:512
	global_load_dwordx4 v[28:31], v[16:17], off offset:576
	v_lshl_add_u64 v[20:21], s[56:57], 0, v[14:15]
	v_lshlrev_b64 v[4:5], 14, v[22:23]
	v_lshl_add_u64 v[4:5], v[20:21], 0, v[4:5]
	global_load_dwordx4 v[172:175], v[4:5], off
	global_load_dwordx4 v[176:179], v[4:5], off offset:64
	global_load_dwordx4 v[186:189], v[4:5], off offset:512
	global_load_dwordx4 v[190:193], v[4:5], off offset:576
	v_lshl_add_u64 v[4:5], v[22:23], 0, 16
	v_lshlrev_b64 v[14:15], 14, v[4:5]
	v_lshl_add_u64 v[14:15], v[20:21], 0, v[14:15]
	global_load_dwordx4 v[194:197], v[14:15], off
	global_load_dwordx4 v[198:201], v[14:15], off offset:64
	global_load_dwordx4 v[202:205], v[14:15], off offset:512
	global_load_dwordx4 v[206:209], v[14:15], off offset:576
	v_lshl_add_u64 v[32:33], v[22:23], 0, 32
	v_lshlrev_b64 v[14:15], 14, v[32:33]
	v_lshl_add_u64 v[14:15], v[20:21], 0, v[14:15]
	global_load_dwordx4 v[210:213], v[14:15], off
	global_load_dwordx4 v[214:217], v[14:15], off offset:64
	global_load_dwordx4 v[218:221], v[14:15], off offset:512
	v_lshl_add_u64 v[242:243], v[22:23], 0, 48
	global_load_dwordx4 v[222:225], v[14:15], off offset:576
	v_lshlrev_b64 v[16:17], 14, v[242:243]
	v_lshl_add_u64 v[16:17], v[20:21], 0, v[16:17]
	global_load_dwordx4 v[226:229], v[16:17], off
	global_load_dwordx4 v[230:233], v[16:17], off offset:64
	global_load_dwordx4 v[234:237], v[16:17], off offset:512
	global_load_dwordx4 v[238:241], v[16:17], off offset:576
	v_lshlrev_b64 v[14:15], 13, v[22:23]
	v_lshlrev_b64 v[2:3], 1, v[2:3]
	v_lshl_add_u64 v[14:15], s[8:9], 0, v[14:15]
	v_lshlrev_b64 v[4:5], 13, v[4:5]
	v_lshl_add_u64 v[244:245], v[14:15], 0, v[2:3]
	v_lshl_add_u64 v[4:5], s[8:9], 0, v[4:5]
	v_lshl_add_u64 v[246:247], v[4:5], 0, v[2:3]
	s_mov_b64 s[38:39], 0x90
	s_waitcnt vmcnt(19)
	v_pk_mul_f32 v[18:19], v[6:7], s[20:21] op_sel_hi:[1,0]
	v_pk_mul_f32 v[16:17], v[8:9], s[20:21] op_sel_hi:[1,0]
	s_waitcnt vmcnt(17)
	v_pk_mul_f32 v[8:9], v[26:27], s[20:21] op_sel_hi:[1,0]
	v_pk_mul_f32 v[12:13], v[12:13], s[20:21] op_sel_hi:[1,0]
	s_waitcnt vmcnt(15)
	v_pk_fma_f32 v[26:27], v[158:159], v[18:19], v[172:173]
	v_pk_mul_f32 v[14:15], v[10:11], s[20:21] op_sel_hi:[1,0]
	v_pk_mul_f32 v[10:11], v[24:25], s[20:21] op_sel_hi:[1,0]
	v_pk_fma_f32 v[24:25], v[160:161], v[16:17], v[174:175]
	v_cvt_pk_bf16_f32 v26, v26, v27
	v_pk_mul_f32 v[4:5], v[30:31], s[20:21] op_sel_hi:[1,0]
	v_cvt_pk_bf16_f32 v27, v24, v25
	v_pk_mul_f32 v[6:7], v[28:29], s[20:21] op_sel_hi:[1,0]
	s_waitcnt vmcnt(14)
	v_pk_fma_f32 v[28:29], v[156:157], v[12:13], v[178:179]
	v_pk_fma_f32 v[30:31], v[154:155], v[14:15], v[176:177]
	global_store_dwordx2 v[244:245], v[26:27], off
	v_cvt_pk_bf16_f32 v26, v30, v31
	v_cvt_pk_bf16_f32 v27, v28, v29
	s_waitcnt vmcnt(14)
	v_pk_fma_f32 v[144:145], v[144:145], v[8:9], v[188:189]
	v_pk_fma_f32 v[142:143], v[142:143], v[10:11], v[186:187]
	global_store_dwordx2 v[244:245], v[26:27], off offset:32
	v_cvt_pk_bf16_f32 v26, v142, v143
	v_cvt_pk_bf16_f32 v27, v144, v145
	s_waitcnt vmcnt(14)
	v_pk_fma_f32 v[140:141], v[140:141], v[4:5], v[192:193]
	v_pk_fma_f32 v[138:139], v[138:139], v[6:7], v[190:191]
	s_waitcnt vmcnt(13)
	v_pk_fma_f32 v[24:25], v[152:153], v[16:17], v[196:197]
	global_store_dwordx2 v[244:245], v[26:27], off offset:256
	v_cvt_pk_bf16_f32 v26, v138, v139
	v_cvt_pk_bf16_f32 v27, v140, v141
	v_pk_fma_f32 v[150:151], v[150:151], v[18:19], v[194:195]
	s_waitcnt vmcnt(13)
	v_pk_fma_f32 v[148:149], v[148:149], v[12:13], v[200:201]
	v_pk_fma_f32 v[146:147], v[146:147], v[14:15], v[198:199]
	global_store_dwordx2 v[244:245], v[26:27], off offset:288
	v_cvt_pk_bf16_f32 v26, v150, v151
	v_cvt_pk_bf16_f32 v27, v24, v25
	global_store_dwordx2 v[246:247], v[26:27], off
	v_cvt_pk_bf16_f32 v24, v146, v147
	v_cvt_pk_bf16_f32 v25, v148, v149
	s_waitcnt vmcnt(14)
	v_pk_fma_f32 v[136:137], v[136:137], v[8:9], v[204:205]
	v_pk_fma_f32 v[134:135], v[134:135], v[10:11], v[202:203]
	global_store_dwordx2 v[246:247], v[24:25], off offset:32
	v_cvt_pk_bf16_f32 v24, v134, v135
	v_cvt_pk_bf16_f32 v25, v136, v137
	s_waitcnt vmcnt(14)
	v_pk_fma_f32 v[132:133], v[132:133], v[4:5], v[208:209]
	v_pk_fma_f32 v[130:131], v[130:131], v[6:7], v[206:207]
	global_store_dwordx2 v[246:247], v[24:25], off offset:256
	v_cvt_pk_bf16_f32 v24, v130, v131
	v_cvt_pk_bf16_f32 v25, v132, v133
	global_store_dwordx2 v[246:247], v[24:25], off offset:288
	v_lshlrev_b64 v[24:25], 13, v[32:33]
	s_waitcnt vmcnt(15)
	v_pk_fma_f32 v[28:29], v[126:127], v[18:19], v[210:211]
	v_lshl_add_u64 v[24:25], s[8:9], 0, v[24:25]
	v_pk_fma_f32 v[26:27], v[128:129], v[16:17], v[212:213]
	v_cvt_pk_bf16_f32 v28, v28, v29
	v_lshl_add_u64 v[24:25], v[24:25], 0, v[2:3]
	v_cvt_pk_bf16_f32 v29, v26, v27
	global_store_dwordx2 v[24:25], v[28:29], off
	s_waitcnt vmcnt(15)
	v_pk_fma_f32 v[28:29], v[122:123], v[14:15], v[214:215]
	v_pk_fma_f32 v[26:27], v[124:125], v[12:13], v[216:217]
	v_cvt_pk_bf16_f32 v28, v28, v29
	v_lshl_add_u64 v[32:33], v[22:23], 0, s[12:13]
	v_cvt_pk_bf16_f32 v29, v26, v27
	global_store_dwordx2 v[24:25], v[28:29], off offset:32
	s_waitcnt vmcnt(15)
	v_pk_fma_f32 v[28:29], v[118:119], v[10:11], v[218:219]
	v_pk_fma_f32 v[26:27], v[120:121], v[8:9], v[220:221]
	v_cvt_pk_bf16_f32 v28, v28, v29
	v_lshl_add_u64 v[150:151], v[22:23], 0, s[38:39]
	v_cvt_pk_bf16_f32 v29, v26, v27
	global_store_dwordx2 v[24:25], v[28:29], off offset:256
	s_waitcnt vmcnt(15)
	v_pk_fma_f32 v[28:29], v[110:111], v[6:7], v[222:223]
	v_pk_fma_f32 v[26:27], v[112:113], v[4:5], v[224:225]
	v_cvt_pk_bf16_f32 v28, v28, v29
	s_mov_b64 s[38:39], 0xa0
	v_cvt_pk_bf16_f32 v29, v26, v27
	global_store_dwordx2 v[24:25], v[28:29], off offset:288
	v_lshlrev_b64 v[24:25], 13, v[242:243]
	s_waitcnt vmcnt(15)
	v_pk_fma_f32 v[28:29], v[114:115], v[18:19], v[226:227]
	v_lshl_add_u64 v[24:25], s[8:9], 0, v[24:25]
	v_pk_fma_f32 v[26:27], v[116:117], v[16:17], v[228:229]
	v_cvt_pk_bf16_f32 v28, v28, v29
	v_lshl_add_u64 v[24:25], v[24:25], 0, v[2:3]
	v_cvt_pk_bf16_f32 v29, v26, v27
	global_store_dwordx2 v[24:25], v[28:29], off
	s_waitcnt vmcnt(15)
	v_pk_fma_f32 v[28:29], v[106:107], v[14:15], v[230:231]
	v_pk_fma_f32 v[26:27], v[108:109], v[12:13], v[232:233]
	v_cvt_pk_bf16_f32 v28, v28, v29
	v_lshlrev_b64 v[106:107], 14, v[150:151]
	v_cvt_pk_bf16_f32 v29, v26, v27
	global_store_dwordx2 v[24:25], v[28:29], off offset:32
	s_waitcnt vmcnt(15)
	v_pk_fma_f32 v[28:29], v[102:103], v[10:11], v[234:235]
	v_pk_fma_f32 v[26:27], v[104:105], v[8:9], v[236:237]
	v_cvt_pk_bf16_f32 v28, v28, v29
	v_lshl_add_u64 v[118:119], v[20:21], 0, v[106:107]
	v_cvt_pk_bf16_f32 v29, v26, v27
	global_store_dwordx2 v[24:25], v[28:29], off offset:256
	s_waitcnt vmcnt(15)
	v_pk_fma_f32 v[28:29], v[98:99], v[6:7], v[238:239]
	v_pk_fma_f32 v[26:27], v[100:101], v[4:5], v[240:241]
	v_cvt_pk_bf16_f32 v28, v28, v29
	v_lshl_add_u64 v[152:153], v[22:23], 0, s[38:39]
	v_cvt_pk_bf16_f32 v29, v26, v27
	global_store_dwordx2 v[24:25], v[28:29], off offset:288
	v_lshlrev_b64 v[24:25], 14, v[32:33]
	v_lshl_add_u64 v[102:103], v[20:21], 0, v[24:25]
	global_load_dwordx4 v[24:27], v[102:103], off
	global_load_dwordx4 v[28:31], v[102:103], off offset:64
	global_load_dwordx4 v[98:101], v[102:103], off offset:512
	s_nop 0
	global_load_dwordx4 v[102:105], v[102:103], off offset:576
	s_nop 0
	global_load_dwordx4 v[106:109], v[118:119], off
	global_load_dwordx4 v[110:113], v[118:119], off offset:64
	global_load_dwordx4 v[114:117], v[118:119], off offset:512
	s_nop 0
	global_load_dwordx4 v[118:121], v[118:119], off offset:576
	v_lshlrev_b64 v[122:123], 14, v[152:153]
	v_lshl_add_u64 v[134:135], v[20:21], 0, v[122:123]
	global_load_dwordx4 v[122:125], v[134:135], off
	global_load_dwordx4 v[126:129], v[134:135], off offset:64
	global_load_dwordx4 v[130:133], v[134:135], off offset:512
	s_nop 0
	global_load_dwordx4 v[134:137], v[134:135], off offset:576
	s_mov_b64 s[38:39], 0xb0
	v_lshl_add_u64 v[154:155], v[22:23], 0, s[38:39]
	v_lshlrev_b64 v[22:23], 14, v[154:155]
	v_lshl_add_u64 v[146:147], v[20:21], 0, v[22:23]
	global_load_dwordx4 v[20:23], v[146:147], off
	global_load_dwordx4 v[138:141], v[146:147], off offset:64
	global_load_dwordx4 v[142:145], v[146:147], off offset:512
	s_nop 0
	global_load_dwordx4 v[146:149], v[146:147], off offset:576
	v_lshlrev_b64 v[32:33], 13, v[32:33]
	v_lshl_add_u64 v[32:33], s[8:9], 0, v[32:33]
	v_lshl_add_u64 v[32:33], v[32:33], 0, v[2:3]
	s_waitcnt vmcnt(15)
	v_pk_fma_f32 v[24:25], v[94:95], v[18:19], v[24:25]
	v_pk_fma_f32 v[26:27], v[96:97], v[16:17], v[26:27]
	v_cvt_pk_bf16_f32 v24, v24, v25
	s_waitcnt vmcnt(14)
	v_pk_fma_f32 v[30:31], v[92:93], v[12:13], v[30:31]
	v_cvt_pk_bf16_f32 v25, v26, v27
	v_pk_fma_f32 v[28:29], v[90:91], v[14:15], v[28:29]
	global_store_dwordx2 v[32:33], v[24:25], off
	v_cvt_pk_bf16_f32 v24, v28, v29
	v_cvt_pk_bf16_f32 v25, v30, v31
	s_waitcnt vmcnt(14)
	v_pk_fma_f32 v[88:89], v[88:89], v[8:9], v[100:101]
	v_pk_fma_f32 v[86:87], v[86:87], v[10:11], v[98:99]
	global_store_dwordx2 v[32:33], v[24:25], off offset:32
	v_cvt_pk_bf16_f32 v24, v86, v87
	v_cvt_pk_bf16_f32 v25, v88, v89
	global_store_dwordx2 v[32:33], v[24:25], off offset:256
	s_waitcnt vmcnt(15)
	v_pk_fma_f32 v[24:25], v[78:79], v[6:7], v[102:103]
	v_pk_fma_f32 v[80:81], v[80:81], v[4:5], v[104:105]
	v_cvt_pk_bf16_f32 v24, v24, v25
	s_waitcnt vmcnt(14)
	v_pk_fma_f32 v[28:29], v[82:83], v[18:19], v[106:107]
	v_cvt_pk_bf16_f32 v25, v80, v81
	global_store_dwordx2 v[32:33], v[24:25], off offset:288
	v_lshlrev_b64 v[24:25], 13, v[150:151]
	v_lshl_add_u64 v[24:25], s[8:9], 0, v[24:25]
	v_pk_fma_f32 v[26:27], v[84:85], v[16:17], v[108:109]
	v_cvt_pk_bf16_f32 v28, v28, v29
	v_lshl_add_u64 v[24:25], v[24:25], 0, v[2:3]
	v_cvt_pk_bf16_f32 v29, v26, v27
	global_store_dwordx2 v[24:25], v[28:29], off
	s_waitcnt vmcnt(15)
	v_pk_fma_f32 v[28:29], v[74:75], v[14:15], v[110:111]
	v_pk_fma_f32 v[26:27], v[76:77], v[12:13], v[112:113]
	v_cvt_pk_bf16_f32 v28, v28, v29
	s_nop 0
	v_cvt_pk_bf16_f32 v29, v26, v27
	global_store_dwordx2 v[24:25], v[28:29], off offset:32
	s_waitcnt vmcnt(15)
	v_pk_fma_f32 v[28:29], v[70:71], v[10:11], v[114:115]
	v_pk_fma_f32 v[26:27], v[72:73], v[8:9], v[116:117]
	v_cvt_pk_bf16_f32 v28, v28, v29
	s_nop 0
	v_cvt_pk_bf16_f32 v29, v26, v27
	global_store_dwordx2 v[24:25], v[28:29], off offset:256
	s_waitcnt vmcnt(15)
	v_pk_fma_f32 v[28:29], v[62:63], v[6:7], v[118:119]
	v_pk_fma_f32 v[26:27], v[64:65], v[4:5], v[120:121]
	v_cvt_pk_bf16_f32 v28, v28, v29
	s_nop 0
	v_cvt_pk_bf16_f32 v29, v26, v27
	global_store_dwordx2 v[24:25], v[28:29], off offset:288
	v_lshlrev_b64 v[24:25], 13, v[152:153]
	s_waitcnt vmcnt(15)
	v_pk_fma_f32 v[28:29], v[66:67], v[18:19], v[122:123]
	v_lshl_add_u64 v[24:25], s[8:9], 0, v[24:25]
	v_pk_fma_f32 v[26:27], v[68:69], v[16:17], v[124:125]
	v_cvt_pk_bf16_f32 v28, v28, v29
	v_lshl_add_u64 v[24:25], v[24:25], 0, v[2:3]
	v_cvt_pk_bf16_f32 v29, v26, v27
	global_store_dwordx2 v[24:25], v[28:29], off
	s_waitcnt vmcnt(15)
	v_pk_fma_f32 v[28:29], v[58:59], v[14:15], v[126:127]
	v_pk_fma_f32 v[26:27], v[60:61], v[12:13], v[128:129]
	v_cvt_pk_bf16_f32 v28, v28, v29
	s_waitcnt vmcnt(12)
	v_pk_fma_f32 v[16:17], v[52:53], v[16:17], v[22:23]
	v_cvt_pk_bf16_f32 v29, v26, v27
	global_store_dwordx2 v[24:25], v[28:29], off offset:32
	v_pk_fma_f32 v[28:29], v[54:55], v[10:11], v[130:131]
	v_pk_fma_f32 v[26:27], v[56:57], v[8:9], v[132:133]
	v_cvt_pk_bf16_f32 v28, v28, v29
	v_pk_fma_f32 v[18:19], v[50:51], v[18:19], v[20:21]
	v_cvt_pk_bf16_f32 v29, v26, v27
	global_store_dwordx2 v[24:25], v[28:29], off offset:256
	v_pk_fma_f32 v[28:29], v[46:47], v[6:7], v[134:135]
	v_pk_fma_f32 v[26:27], v[48:49], v[4:5], v[136:137]
	v_cvt_pk_bf16_f32 v28, v28, v29
	s_waitcnt vmcnt(13)
	v_pk_fma_f32 v[14:15], v[42:43], v[14:15], v[138:139]
	v_cvt_pk_bf16_f32 v29, v26, v27
	global_store_dwordx2 v[24:25], v[28:29], off offset:288
	v_lshlrev_b64 v[24:25], 13, v[154:155]
	v_cvt_pk_bf16_f32 v18, v18, v19
	v_cvt_pk_bf16_f32 v19, v16, v17
	v_lshl_add_u64 v[16:17], s[8:9], 0, v[24:25]
	v_lshl_add_u64 v[2:3], v[16:17], 0, v[2:3]
	s_waitcnt vmcnt(13)
	v_pk_fma_f32 v[10:11], v[38:39], v[10:11], v[142:143]
	s_waitcnt vmcnt(12)
	v_pk_fma_f32 v[6:7], v[34:35], v[6:7], v[146:147]
	global_store_dwordx2 v[2:3], v[18:19], off
	v_pk_fma_f32 v[12:13], v[44:45], v[12:13], v[140:141]
	v_cvt_pk_bf16_f32 v14, v14, v15
	v_pk_fma_f32 v[8:9], v[40:41], v[8:9], v[144:145]
	v_cvt_pk_bf16_f32 v15, v12, v13
	global_store_dwordx2 v[2:3], v[14:15], off offset:32
	v_cvt_pk_bf16_f32 v10, v10, v11
	v_cvt_pk_bf16_f32 v11, v8, v9
	global_store_dwordx2 v[2:3], v[10:11], off offset:256
	v_pk_fma_f32 v[4:5], v[36:37], v[4:5], v[148:149]
	v_cvt_pk_bf16_f32 v6, v6, v7
	s_nop 0
	v_cvt_pk_bf16_f32 v7, v4, v5
	global_store_dwordx2 v[2:3], v[6:7], off offset:288

.LBB0_1783:
	s_nop 15
	s_nop 7
	v_mov_b32_e32 v2, v180
	v_mov_b32_e32 v0, v181
	s_andn2_b64 vcc, exec, s[12:13]
	s_cbranch_vccnz .LBB0_1785
	s_lshl_b32 s25, s25, 8
	s_or_b32 s25, s25, s47
	v_lshl_add_u32 v12, v0, 2, s25
	s_ashr_i32 s25, s24, 4
	s_mul_hi_i32 s27, s25, 0x18000
	s_mul_i32 s25, s25, 0x18000
	s_add_u32 s26, s44, s25
	s_addc_u32 s27, s45, s27
	s_ashr_i32 s25, s24, 31
	s_lshl_b64 s[24:25], s[24:25], 8
	s_add_u32 s24, s24, s46
	v_ashrrev_i32_e32 v13, 31, v12
	v_ashrrev_i32_e32 v3, 31, v2
	s_addc_u32 s25, s25, 0
	v_lshlrev_b64 v[0:1], 2, v[12:13]
	v_lshl_add_u64 v[20:21], s[24:25], 0, v[2:3]
	v_lshl_add_u64 v[14:15], s[26:27], 0, v[0:1]
	v_lshl_add_u64 v[18:19], v[12:13], 1, s[6:7]
	v_lshlrev_b64 v[2:3], 13, v[20:21]
	global_load_dwordx4 v[4:7], v[14:15], off
	global_load_dwordx4 v[8:11], v[14:15], off offset:64
	global_load_dwordx4 v[24:27], v[14:15], off offset:512
	global_load_dwordx4 v[28:31], v[14:15], off offset:576
	v_lshl_add_u64 v[2:3], v[18:19], 0, v[2:3]
	global_load_dwordx2 v[172:173], v[2:3], off
	global_load_dwordx2 v[174:175], v[2:3], off offset:32
	global_load_dwordx2 v[176:177], v[2:3], off offset:256
	global_load_dwordx2 v[178:179], v[2:3], off offset:288
	v_lshl_add_u64 v[2:3], v[20:21], 0, 16
	v_lshlrev_b64 v[12:13], 13, v[2:3]
	v_lshl_add_u64 v[12:13], v[18:19], 0, v[12:13]
	global_load_dwordx2 v[186:187], v[12:13], off
	global_load_dwordx2 v[188:189], v[12:13], off offset:32
	global_load_dwordx2 v[190:191], v[12:13], off offset:256
	global_load_dwordx2 v[192:193], v[12:13], off offset:288
	v_lshl_add_u64 v[194:195], v[20:21], 0, 32
	v_lshlrev_b64 v[14:15], 13, v[194:195]
	v_lshl_add_u64 v[14:15], v[18:19], 0, v[14:15]
	global_load_dwordx2 v[196:197], v[14:15], off
	v_lshl_add_u64 v[22:23], v[20:21], 0, 48
	v_lshlrev_b64 v[16:17], 13, v[22:23]
	v_lshlrev_b64 v[198:199], 14, v[2:3]
	v_lshl_add_u64 v[2:3], v[18:19], 0, v[16:17]
	global_load_dwordx2 v[202:203], v[14:15], off offset:32
	global_load_dwordx2 v[204:205], v[14:15], off offset:256
	global_load_dwordx2 v[206:207], v[14:15], off offset:288
	global_load_dwordx2 v[208:209], v[2:3], off
	global_load_dwordx2 v[210:211], v[2:3], off offset:32
	global_load_dwordx2 v[212:213], v[2:3], off offset:256
	global_load_dwordx2 v[214:215], v[2:3], off offset:288
	v_readlane_b32 s24, v254, 0
	v_readlane_b32 s26, v254, 2
	v_readlane_b32 s27, v254, 3
	v_readlane_b32 s30, v254, 6
	v_readlane_b32 s31, v254, 7
	v_lshlrev_b64 v[12:13], 14, v[20:21]
	s_mov_b64 s[26:27], s[30:31]
	v_lshl_add_u64 v[12:13], s[26:27], 0, v[12:13]
	v_lshl_add_u64 v[200:201], v[12:13], 0, v[0:1]
	v_readlane_b32 s25, v254, 1
	v_readlane_b32 s28, v254, 4
	v_readlane_b32 s29, v254, 5
	s_waitcnt vmcnt(19)
	v_pk_mul_f32 v[16:17], v[6:7], s[14:15] op_sel_hi:[1,0]
	v_pk_mul_f32 v[14:15], v[4:5], s[14:15] op_sel_hi:[1,0]
	s_waitcnt vmcnt(18)
	v_pk_mul_f32 v[12:13], v[10:11], s[14:15] op_sel_hi:[1,0]
	v_pk_mul_f32 v[10:11], v[8:9], s[14:15] op_sel_hi:[1,0]
	s_waitcnt vmcnt(17)
	v_pk_mul_f32 v[8:9], v[26:27], s[14:15] op_sel_hi:[1,0]
	v_pk_mul_f32 v[6:7], v[24:25], s[14:15] op_sel_hi:[1,0]
	s_waitcnt vmcnt(16)
	v_pk_mul_f32 v[2:3], v[28:29], s[14:15] op_sel_hi:[1,0]
	s_waitcnt vmcnt(15)
	v_lshlrev_b32_e32 v24, 16, v172
	v_and_b32_e32 v25, 0xffff0000, v172
	v_lshlrev_b32_e32 v26, 16, v173
	v_and_b32_e32 v27, 0xffff0000, v173
	s_waitcnt vmcnt(14)
	v_lshlrev_b32_e32 v28, 16, v174
	v_and_b32_e32 v29, 0xffff0000, v174
	v_pk_mul_f32 v[4:5], v[30:31], s[14:15] op_sel_hi:[1,0]
	v_lshlrev_b32_e32 v30, 16, v175
	v_and_b32_e32 v31, 0xffff0000, v175
	s_waitcnt vmcnt(13)
	v_lshlrev_b32_e32 v172, 16, v176
	v_and_b32_e32 v173, 0xffff0000, v176
	v_lshlrev_b32_e32 v174, 16, v177
	v_and_b32_e32 v175, 0xffff0000, v177
	s_waitcnt vmcnt(12)
	v_lshlrev_b32_e32 v176, 16, v178
	v_and_b32_e32 v177, 0xffff0000, v178
	v_lshlrev_b32_e32 v178, 16, v179
	v_and_b32_e32 v179, 0xffff0000, v179
	v_pk_fma_f32 v[26:27], v[158:159], v[16:17], v[26:27]
	v_pk_fma_f32 v[24:25], v[156:157], v[14:15], v[24:25]
	v_pk_fma_f32 v[28:29], v[152:153], v[10:11], v[28:29]
	v_pk_fma_f32 v[30:31], v[154:155], v[12:13], v[30:31]
	v_pk_fma_f32 v[146:147], v[146:147], v[8:9], v[174:175]
	v_pk_fma_f32 v[144:145], v[144:145], v[6:7], v[172:173]
	v_pk_fma_f32 v[142:143], v[142:143], v[4:5], v[178:179]
	v_pk_fma_f32 v[140:141], v[140:141], v[2:3], v[176:177]
	s_waitcnt vmcnt(11)
	v_lshlrev_b32_e32 v152, 16, v186
	v_and_b32_e32 v153, 0xffff0000, v186
	v_lshlrev_b32_e32 v154, 16, v187
	v_and_b32_e32 v155, 0xffff0000, v187
	global_store_dwordx4 v[200:201], v[24:27], off nt
	global_store_dwordx4 v[200:201], v[28:31], off offset:64 nt
	global_store_dwordx4 v[200:201], v[144:147], off offset:512 nt
	global_store_dwordx4 v[200:201], v[140:143], off offset:576 nt
	v_lshl_add_u64 v[28:29], s[26:27], 0, v[198:199]
	v_pk_fma_f32 v[26:27], v[150:151], v[16:17], v[154:155]
	v_pk_fma_f32 v[24:25], v[148:149], v[14:15], v[152:153]
	v_lshl_add_u64 v[28:29], v[28:29], 0, v[0:1]
	global_store_dwordx4 v[28:29], v[24:27], off nt
	s_nop 1
	s_waitcnt vmcnt(15)
	v_lshlrev_b32_e32 v24, 16, v188
	v_and_b32_e32 v25, 0xffff0000, v188
	v_lshlrev_b32_e32 v26, 16, v189
	v_and_b32_e32 v27, 0xffff0000, v189
	v_pk_fma_f32 v[26:27], v[138:139], v[12:13], v[26:27]
	v_pk_fma_f32 v[24:25], v[136:137], v[10:11], v[24:25]
	global_store_dwordx4 v[28:29], v[24:27], off offset:64 nt
	s_nop 1
	s_waitcnt vmcnt(15)
	v_lshlrev_b32_e32 v24, 16, v190
	v_and_b32_e32 v25, 0xffff0000, v190
	v_lshlrev_b32_e32 v26, 16, v191
	v_and_b32_e32 v27, 0xffff0000, v191
	v_pk_fma_f32 v[26:27], v[134:135], v[8:9], v[26:27]
	v_pk_fma_f32 v[24:25], v[132:133], v[6:7], v[24:25]
	global_store_dwordx4 v[28:29], v[24:27], off offset:512 nt
	s_nop 1
	s_waitcnt vmcnt(15)
	v_lshlrev_b32_e32 v24, 16, v192
	v_and_b32_e32 v25, 0xffff0000, v192
	v_lshlrev_b32_e32 v26, 16, v193
	v_and_b32_e32 v27, 0xffff0000, v193
	v_pk_fma_f32 v[26:27], v[126:127], v[4:5], v[26:27]
	v_pk_fma_f32 v[24:25], v[124:125], v[2:3], v[24:25]
	global_store_dwordx4 v[28:29], v[24:27], off offset:576 nt
	v_lshlrev_b64 v[28:29], 14, v[194:195]
	v_lshl_add_u64 v[28:29], s[26:27], 0, v[28:29]
	s_waitcnt vmcnt(15)
	v_lshlrev_b32_e32 v24, 16, v196
	v_and_b32_e32 v25, 0xffff0000, v196
	v_lshlrev_b32_e32 v26, 16, v197
	v_and_b32_e32 v27, 0xffff0000, v197
	v_pk_fma_f32 v[26:27], v[130:131], v[16:17], v[26:27]
	v_pk_fma_f32 v[24:25], v[128:129], v[14:15], v[24:25]
	v_lshl_add_u64 v[28:29], v[28:29], 0, v[0:1]
	global_store_dwordx4 v[28:29], v[24:27], off nt
	s_nop 1
	s_waitcnt vmcnt(15)
	v_lshlrev_b32_e32 v24, 16, v202
	v_and_b32_e32 v25, 0xffff0000, v202
	v_lshlrev_b32_e32 v26, 16, v203
	v_and_b32_e32 v27, 0xffff0000, v203
	v_pk_fma_f32 v[26:27], v[122:123], v[12:13], v[26:27]
	v_pk_fma_f32 v[24:25], v[120:121], v[10:11], v[24:25]
	global_store_dwordx4 v[28:29], v[24:27], off offset:64 nt
	s_nop 1
	s_waitcnt vmcnt(15)
	v_lshlrev_b32_e32 v24, 16, v204
	v_and_b32_e32 v25, 0xffff0000, v204
	v_lshlrev_b32_e32 v26, 16, v205
	v_and_b32_e32 v27, 0xffff0000, v205
	v_pk_fma_f32 v[26:27], v[118:119], v[8:9], v[26:27]
	v_pk_fma_f32 v[24:25], v[116:117], v[6:7], v[24:25]
	global_store_dwordx4 v[28:29], v[24:27], off offset:512 nt
	v_lshl_add_u64 v[118:119], v[20:21], 0, s[20:21]
	s_nop 0
	s_waitcnt vmcnt(15)
	v_lshlrev_b32_e32 v24, 16, v206
	v_and_b32_e32 v25, 0xffff0000, v206
	v_lshlrev_b32_e32 v26, 16, v207
	v_and_b32_e32 v27, 0xffff0000, v207
	v_pk_fma_f32 v[26:27], v[110:111], v[4:5], v[26:27]
	v_pk_fma_f32 v[24:25], v[108:109], v[2:3], v[24:25]
	global_store_dwordx4 v[28:29], v[24:27], off offset:576 nt
	v_lshl_add_u64 v[108:109], v[20:21], 0, s[18:19]
	s_nop 0
	v_lshlrev_b64 v[26:27], 14, v[22:23]
	s_waitcnt vmcnt(15)
	v_lshlrev_b32_e32 v22, 16, v208
	v_and_b32_e32 v23, 0xffff0000, v208
	v_lshlrev_b32_e32 v24, 16, v209
	v_and_b32_e32 v25, 0xffff0000, v209
	v_lshl_add_u64 v[26:27], s[26:27], 0, v[26:27]
	v_pk_fma_f32 v[24:25], v[114:115], v[16:17], v[24:25]
	v_pk_fma_f32 v[22:23], v[112:113], v[14:15], v[22:23]
	v_lshl_add_u64 v[26:27], v[26:27], 0, v[0:1]
	global_store_dwordx4 v[26:27], v[22:25], off nt
	s_nop 1
	s_waitcnt vmcnt(15)
	v_lshlrev_b32_e32 v22, 16, v210
	v_and_b32_e32 v23, 0xffff0000, v210
	v_lshlrev_b32_e32 v24, 16, v211
	v_and_b32_e32 v25, 0xffff0000, v211
	v_pk_fma_f32 v[24:25], v[106:107], v[12:13], v[24:25]
	v_pk_fma_f32 v[22:23], v[104:105], v[10:11], v[22:23]
	global_store_dwordx4 v[26:27], v[22:25], off offset:64 nt
	s_nop 1
	s_waitcnt vmcnt(15)
	v_lshlrev_b32_e32 v22, 16, v212
	v_and_b32_e32 v23, 0xffff0000, v212
	v_lshlrev_b32_e32 v24, 16, v213
	v_and_b32_e32 v25, 0xffff0000, v213
	v_pk_fma_f32 v[24:25], v[102:103], v[8:9], v[24:25]
	v_pk_fma_f32 v[22:23], v[100:101], v[6:7], v[22:23]
	global_store_dwordx4 v[26:27], v[22:25], off offset:512 nt
	s_nop 1
	s_waitcnt vmcnt(15)
	v_lshlrev_b32_e32 v22, 16, v214
	v_and_b32_e32 v23, 0xffff0000, v214
	v_lshlrev_b32_e32 v24, 16, v215
	v_and_b32_e32 v25, 0xffff0000, v215
	v_pk_fma_f32 v[24:25], v[98:99], v[4:5], v[24:25]
	v_pk_fma_f32 v[22:23], v[96:97], v[2:3], v[22:23]
	global_store_dwordx4 v[26:27], v[22:25], off offset:576 nt
	v_lshl_add_u64 v[98:99], v[20:21], 0, s[16:17]
	s_nop 0
	v_lshl_add_u64 v[22:23], v[20:21], 0, s[8:9]
	v_lshlrev_b64 v[24:25], 13, v[22:23]
	v_lshl_add_u64 v[24:25], v[18:19], 0, v[24:25]
	global_load_dwordx2 v[26:27], v[24:25], off
	global_load_dwordx2 v[28:29], v[24:25], off offset:32
	global_load_dwordx2 v[30:31], v[24:25], off offset:256
	global_load_dwordx2 v[96:97], v[24:25], off offset:288
	v_lshlrev_b64 v[24:25], 13, v[98:99]
	v_lshl_add_u64 v[24:25], v[18:19], 0, v[24:25]
	global_load_dwordx2 v[100:101], v[24:25], off
	global_load_dwordx2 v[102:103], v[24:25], off offset:32
	global_load_dwordx2 v[104:105], v[24:25], off offset:256
	global_load_dwordx2 v[106:107], v[24:25], off offset:288
	v_lshlrev_b64 v[24:25], 13, v[108:109]
	v_lshl_add_u64 v[24:25], v[18:19], 0, v[24:25]
	global_load_dwordx2 v[110:111], v[24:25], off
	global_load_dwordx2 v[112:113], v[24:25], off offset:32
	global_load_dwordx2 v[114:115], v[24:25], off offset:256
	global_load_dwordx2 v[116:117], v[24:25], off offset:288
	v_lshlrev_b64 v[20:21], 13, v[118:119]
	v_lshl_add_u64 v[18:19], v[18:19], 0, v[20:21]
	global_load_dwordx2 v[120:121], v[18:19], off
	global_load_dwordx2 v[122:123], v[18:19], off offset:32
	global_load_dwordx2 v[20:21], v[18:19], off offset:256
	s_nop 0
	global_load_dwordx2 v[18:19], v[18:19], off offset:288
	v_lshlrev_b64 v[124:125], 14, v[22:23]
	s_waitcnt vmcnt(15)
	v_lshlrev_b32_e32 v22, 16, v26
	v_and_b32_e32 v23, 0xffff0000, v26
	v_lshlrev_b32_e32 v24, 16, v27
	v_and_b32_e32 v25, 0xffff0000, v27
	v_lshl_add_u64 v[26:27], s[26:27], 0, v[124:125]
	v_pk_fma_f32 v[24:25], v[94:95], v[16:17], v[24:25]
	v_pk_fma_f32 v[22:23], v[92:93], v[14:15], v[22:23]
	v_lshl_add_u64 v[26:27], v[26:27], 0, v[0:1]
	global_store_dwordx4 v[26:27], v[22:25], off nt
	s_waitcnt vmcnt(15)
	s_nop 0
	v_lshlrev_b32_e32 v22, 16, v28
	v_and_b32_e32 v23, 0xffff0000, v28
	v_lshlrev_b32_e32 v24, 16, v29
	v_and_b32_e32 v25, 0xffff0000, v29
	v_pk_fma_f32 v[24:25], v[90:91], v[12:13], v[24:25]
	v_pk_fma_f32 v[22:23], v[88:89], v[10:11], v[22:23]
	global_store_dwordx4 v[26:27], v[22:25], off offset:64 nt
	s_waitcnt vmcnt(15)
	s_nop 0
	v_lshlrev_b32_e32 v22, 16, v30
	v_and_b32_e32 v23, 0xffff0000, v30
	v_lshlrev_b32_e32 v24, 16, v31
	v_and_b32_e32 v25, 0xffff0000, v31
	v_pk_fma_f32 v[24:25], v[86:87], v[8:9], v[24:25]
	v_pk_fma_f32 v[22:23], v[84:85], v[6:7], v[22:23]
	global_store_dwordx4 v[26:27], v[22:25], off offset:512 nt
	s_waitcnt vmcnt(15)
	s_nop 0
	v_lshlrev_b32_e32 v22, 16, v96
	v_and_b32_e32 v23, 0xffff0000, v96
	v_lshlrev_b32_e32 v24, 16, v97
	v_and_b32_e32 v25, 0xffff0000, v97
	v_pk_fma_f32 v[24:25], v[78:79], v[4:5], v[24:25]
	v_pk_fma_f32 v[22:23], v[76:77], v[2:3], v[22:23]
	global_store_dwordx4 v[26:27], v[22:25], off offset:576 nt
	v_lshlrev_b64 v[26:27], 14, v[98:99]
	v_lshl_add_u64 v[26:27], s[26:27], 0, v[26:27]
	s_waitcnt vmcnt(15)
	v_lshlrev_b32_e32 v22, 16, v100
	v_and_b32_e32 v23, 0xffff0000, v100
	v_lshlrev_b32_e32 v24, 16, v101
	v_and_b32_e32 v25, 0xffff0000, v101
	v_pk_fma_f32 v[24:25], v[82:83], v[16:17], v[24:25]
	v_pk_fma_f32 v[22:23], v[80:81], v[14:15], v[22:23]
	v_lshl_add_u64 v[26:27], v[26:27], 0, v[0:1]
	global_store_dwordx4 v[26:27], v[22:25], off nt
	s_waitcnt vmcnt(15)
	s_nop 0
	v_lshlrev_b32_e32 v22, 16, v102
	v_and_b32_e32 v23, 0xffff0000, v102
	v_lshlrev_b32_e32 v24, 16, v103
	v_and_b32_e32 v25, 0xffff0000, v103
	v_pk_fma_f32 v[24:25], v[74:75], v[12:13], v[24:25]
	v_pk_fma_f32 v[22:23], v[72:73], v[10:11], v[22:23]
	global_store_dwordx4 v[26:27], v[22:25], off offset:64 nt
	s_waitcnt vmcnt(15)
	s_nop 0
	v_lshlrev_b32_e32 v22, 16, v104
	v_and_b32_e32 v23, 0xffff0000, v104
	v_lshlrev_b32_e32 v24, 16, v105
	v_and_b32_e32 v25, 0xffff0000, v105
	v_pk_fma_f32 v[24:25], v[70:71], v[8:9], v[24:25]
	v_pk_fma_f32 v[22:23], v[68:69], v[6:7], v[22:23]
	global_store_dwordx4 v[26:27], v[22:25], off offset:512 nt
	s_waitcnt vmcnt(15)
	s_nop 0
	v_lshlrev_b32_e32 v22, 16, v106
	v_and_b32_e32 v23, 0xffff0000, v106
	v_lshlrev_b32_e32 v24, 16, v107
	v_and_b32_e32 v25, 0xffff0000, v107
	v_pk_fma_f32 v[24:25], v[62:63], v[4:5], v[24:25]
	v_pk_fma_f32 v[22:23], v[60:61], v[2:3], v[22:23]
	global_store_dwordx4 v[26:27], v[22:25], off offset:576 nt
	v_lshlrev_b64 v[26:27], 14, v[108:109]
	v_lshl_add_u64 v[26:27], s[26:27], 0, v[26:27]
	s_waitcnt vmcnt(15)
	v_lshlrev_b32_e32 v22, 16, v110
	v_and_b32_e32 v23, 0xffff0000, v110
	v_lshlrev_b32_e32 v24, 16, v111
	v_and_b32_e32 v25, 0xffff0000, v111
	v_pk_fma_f32 v[24:25], v[66:67], v[16:17], v[24:25]
	v_pk_fma_f32 v[22:23], v[64:65], v[14:15], v[22:23]
	v_lshl_add_u64 v[26:27], v[26:27], 0, v[0:1]
	global_store_dwordx4 v[26:27], v[22:25], off nt
	s_waitcnt vmcnt(15)
	s_nop 0
	v_lshlrev_b32_e32 v22, 16, v112
	v_and_b32_e32 v23, 0xffff0000, v112
	v_lshlrev_b32_e32 v24, 16, v113
	v_and_b32_e32 v25, 0xffff0000, v113
	v_pk_fma_f32 v[24:25], v[58:59], v[12:13], v[24:25]
	v_pk_fma_f32 v[22:23], v[56:57], v[10:11], v[22:23]
	global_store_dwordx4 v[26:27], v[22:25], off offset:64 nt
	s_waitcnt vmcnt(15)
	s_nop 0
	v_lshlrev_b32_e32 v22, 16, v114
	v_and_b32_e32 v23, 0xffff0000, v114
	v_lshlrev_b32_e32 v24, 16, v115
	v_and_b32_e32 v25, 0xffff0000, v115
	v_pk_fma_f32 v[24:25], v[54:55], v[8:9], v[24:25]
	v_pk_fma_f32 v[22:23], v[52:53], v[6:7], v[22:23]
	global_store_dwordx4 v[26:27], v[22:25], off offset:512 nt
	s_waitcnt vmcnt(15)
	s_nop 0
	v_lshlrev_b32_e32 v22, 16, v116
	v_and_b32_e32 v23, 0xffff0000, v116
	v_lshlrev_b32_e32 v24, 16, v117
	v_and_b32_e32 v25, 0xffff0000, v117
	v_pk_fma_f32 v[24:25], v[46:47], v[4:5], v[24:25]
	v_pk_fma_f32 v[22:23], v[44:45], v[2:3], v[22:23]
	global_store_dwordx4 v[26:27], v[22:25], off offset:576 nt
	s_waitcnt vmcnt(15)
	v_lshlrev_b32_e32 v26, 16, v121
	v_and_b32_e32 v27, 0xffff0000, v121
	v_lshlrev_b64 v[22:23], 14, v[118:119]
	v_lshlrev_b32_e32 v24, 16, v120
	v_and_b32_e32 v25, 0xffff0000, v120
	v_lshl_add_u64 v[22:23], s[26:27], 0, v[22:23]
	v_pk_fma_f32 v[16:17], v[50:51], v[16:17], v[26:27]
	v_pk_fma_f32 v[14:15], v[48:49], v[14:15], v[24:25]
	v_lshl_add_u64 v[0:1], v[22:23], 0, v[0:1]
	global_store_dwordx4 v[0:1], v[14:17], off nt
	s_waitcnt vmcnt(15)
	s_nop 0
	v_lshlrev_b32_e32 v14, 16, v122
	v_and_b32_e32 v15, 0xffff0000, v122
	v_lshlrev_b32_e32 v16, 16, v123
	v_and_b32_e32 v17, 0xffff0000, v123
	v_pk_fma_f32 v[12:13], v[42:43], v[12:13], v[16:17]
	v_pk_fma_f32 v[10:11], v[40:41], v[10:11], v[14:15]
	global_store_dwordx4 v[0:1], v[10:13], off offset:64 nt
	s_waitcnt vmcnt(15)
	s_nop 0
	v_lshlrev_b32_e32 v10, 16, v20
	v_and_b32_e32 v11, 0xffff0000, v20
	v_lshlrev_b32_e32 v12, 16, v21
	v_and_b32_e32 v13, 0xffff0000, v21
	v_pk_fma_f32 v[8:9], v[38:39], v[8:9], v[12:13]
	v_pk_fma_f32 v[6:7], v[36:37], v[6:7], v[10:11]
	global_store_dwordx4 v[0:1], v[6:9], off offset:512 nt
	s_waitcnt vmcnt(15)
	s_nop 0
	v_lshlrev_b32_e32 v6, 16, v18
	v_and_b32_e32 v7, 0xffff0000, v18
	v_lshlrev_b32_e32 v8, 16, v19
	v_and_b32_e32 v9, 0xffff0000, v19
	v_pk_fma_f32 v[4:5], v[34:35], v[4:5], v[8:9]
	v_pk_fma_f32 v[2:3], v[32:33], v[2:3], v[6:7]
	global_store_dwordx4 v[0:1], v[2:5], off offset:576 nt
